# v46: rope_item loops 1 and 3 (both E2 copies) fully unrolled with all iterations' loads issued first in renamed register sets, counted waits
# speedup vs baseline: 1.0003x; 1.0003x over previous
.LBB0_1483:
	s_mov_b32 s1, 0x0
	v_add_u32_e32 v0, s1, v8
	v_ashrrev_i32_e32 v0, 5, v0
	v_add_u32_e32 v3, s16, v0
	v_lshl_or_b32 v18, v3, 5, v2
	v_add_u32_e32 v0, s3, v0
	v_ashrrev_i32_e32 v19, 31, v18
	v_mad_i64_i32 v[6:7], s[4:5], v0, s84, v[4:5]
	v_lshlrev_b64 v[18:19], 2, v[18:19]
	global_load_dwordx4 v[10:13], v[6:7], off offset:2048
	global_load_dwordx4 v[14:17], v[6:7], off offset:2112
	v_lshl_add_u64 v[22:23], s[8:9], 0, v[18:19]
	v_lshl_add_u64 v[30:31], s[10:11], 0, v[18:19]
	global_load_dwordx4 v[18:21], v[22:23], off offset:16
	s_nop 0
	global_load_dwordx4 v[22:25], v[22:23], off
	s_nop 0
	global_load_dwordx4 v[26:29], v[30:31], off offset:16
	s_nop 0
	global_load_dwordx4 v[30:33], v[30:31], off
	s_mov_b32 s1, 0x200
	v_add_u32_e32 v50, s1, v8
	v_ashrrev_i32_e32 v50, 5, v50
	v_add_u32_e32 v53, s16, v50
	v_lshl_or_b32 v68, v53, 5, v2
	v_add_u32_e32 v50, s3, v50
	v_ashrrev_i32_e32 v69, 31, v68
	v_mad_i64_i32 v[56:57], s[4:5], v50, s84, v[4:5]
	v_lshlrev_b64 v[68:69], 2, v[68:69]
	global_load_dwordx4 v[60:63], v[56:57], off offset:2048
	global_load_dwordx4 v[64:67], v[56:57], off offset:2112
	v_lshl_add_u64 v[72:73], s[8:9], 0, v[68:69]
	v_lshl_add_u64 v[80:81], s[10:11], 0, v[68:69]
	global_load_dwordx4 v[68:71], v[72:73], off offset:16
	s_nop 0
	global_load_dwordx4 v[72:75], v[72:73], off
	s_nop 0
	global_load_dwordx4 v[76:79], v[80:81], off offset:16
	s_nop 0
	global_load_dwordx4 v[80:83], v[80:81], off
	s_mov_b32 s1, 0x400
	v_add_u32_e32 v90, s1, v8
	v_ashrrev_i32_e32 v90, 5, v90
	v_add_u32_e32 v93, s16, v90
	v_lshl_or_b32 v108, v93, 5, v2
	v_add_u32_e32 v90, s3, v90
	v_ashrrev_i32_e32 v109, 31, v108
	v_mad_i64_i32 v[96:97], s[4:5], v90, s84, v[4:5]
	v_lshlrev_b64 v[108:109], 2, v[108:109]
	global_load_dwordx4 v[100:103], v[96:97], off offset:2048
	global_load_dwordx4 v[104:107], v[96:97], off offset:2112
	v_lshl_add_u64 v[112:113], s[8:9], 0, v[108:109]
	v_lshl_add_u64 v[120:121], s[10:11], 0, v[108:109]
	global_load_dwordx4 v[108:111], v[112:113], off offset:16
	s_nop 0
	global_load_dwordx4 v[112:115], v[112:113], off
	s_nop 0
	global_load_dwordx4 v[116:119], v[120:121], off offset:16
	s_nop 0
	global_load_dwordx4 v[120:123], v[120:121], off
	s_mov_b32 s1, 0x600
	v_add_u32_e32 v196, s1, v8
	v_ashrrev_i32_e32 v196, 5, v196
	v_add_u32_e32 v199, s16, v196
	v_lshl_or_b32 v214, v199, 5, v2
	v_add_u32_e32 v196, s3, v196
	v_ashrrev_i32_e32 v215, 31, v214
	v_mad_i64_i32 v[202:203], s[4:5], v196, s84, v[4:5]
	v_lshlrev_b64 v[214:215], 2, v[214:215]
	global_load_dwordx4 v[206:209], v[202:203], off offset:2048
	global_load_dwordx4 v[210:213], v[202:203], off offset:2112
	v_lshl_add_u64 v[218:219], s[8:9], 0, v[214:215]
	v_lshl_add_u64 v[226:227], s[10:11], 0, v[214:215]
	global_load_dwordx4 v[214:217], v[218:219], off offset:16
	s_nop 0
	global_load_dwordx4 v[218:221], v[218:219], off
	s_nop 0
	global_load_dwordx4 v[222:225], v[226:227], off offset:16
	s_nop 0
	global_load_dwordx4 v[226:229], v[226:227], off
	s_waitcnt vmcnt(18)
	v_lshlrev_b32_e32 v34, 16, v10
	v_and_b32_e32 v35, 0xffff0000, v10
	v_lshlrev_b32_e32 v36, 16, v14
	v_and_b32_e32 v37, 0xffff0000, v14
	v_pk_mul_f32 v[38:39], v[30:31], v[36:37]
	v_pk_mul_f32 v[30:31], v[30:31], v[34:35]
	v_lshlrev_b32_e32 v14, 16, v15
	v_and_b32_e32 v15, 0xffff0000, v15
	v_pk_fma_f32 v[38:39], v[22:23], v[34:35], v[38:39] neg_lo:[0,0,1] neg_hi:[0,0,1]
	v_pk_fma_f32 v[22:23], v[22:23], v[36:37], v[30:31]
	v_lshlrev_b32_e32 v10, 16, v11
	v_and_b32_e32 v11, 0xffff0000, v11
	v_pk_mul_f32 v[30:31], v[32:33], v[14:15]
	v_pk_mul_f32 v[38:39], v[38:39], s[86:87] op_sel_hi:[1,0]
	v_pk_fma_f32 v[30:31], v[24:25], v[10:11], v[30:31] neg_lo:[0,0,1] neg_hi:[0,0,1]
	v_pk_mul_f32 v[10:11], v[32:33], v[10:11]
	v_pk_mul_f32 v[30:31], v[30:31], s[86:87] op_sel_hi:[1,0]
	v_pk_fma_f32 v[10:11], v[24:25], v[14:15], v[10:11]
	v_lshlrev_b32_e32 v24, 16, v16
	v_and_b32_e32 v25, 0xffff0000, v16
	v_pk_mul_f32 v[14:15], v[10:11], s[86:87] op_sel_hi:[1,0]
	v_lshlrev_b32_e32 v10, 16, v12
	v_and_b32_e32 v11, 0xffff0000, v12
	v_pk_mul_f32 v[32:33], v[26:27], v[24:25]
	v_lshlrev_b32_e32 v12, 16, v17
	v_pk_fma_f32 v[32:33], v[18:19], v[10:11], v[32:33] neg_lo:[0,0,1] neg_hi:[0,0,1]
	v_pk_mul_f32 v[10:11], v[26:27], v[10:11]
	v_pk_mul_f32 v[32:33], v[32:33], s[86:87] op_sel_hi:[1,0]
	v_pk_fma_f32 v[10:11], v[18:19], v[24:25], v[10:11]
	v_pk_mul_f32 v[22:23], v[22:23], s[86:87] op_sel_hi:[1,0]
	v_pk_mul_f32 v[18:19], v[10:11], s[86:87] op_sel_hi:[1,0]
	v_lshlrev_b32_e32 v10, 16, v13
	v_and_b32_e32 v11, 0xffff0000, v13
	v_and_b32_e32 v13, 0xffff0000, v17
	v_pk_mul_f32 v[16:17], v[28:29], v[12:13]
	s_nop 0
	v_pk_fma_f32 v[16:17], v[20:21], v[10:11], v[16:17] neg_lo:[0,0,1] neg_hi:[0,0,1]
	v_pk_mul_f32 v[10:11], v[28:29], v[10:11]
	v_pk_mul_f32 v[16:17], v[16:17], s[86:87] op_sel_hi:[1,0]
	v_pk_fma_f32 v[10:11], v[20:21], v[12:13], v[10:11]
	v_cvt_pk_bf16_f32 v12, v32, v33
	v_pk_mul_f32 v[20:21], v[10:11], s[86:87] op_sel_hi:[1,0]
	v_cvt_pk_bf16_f32 v10, v38, v39
	v_cvt_pk_bf16_f32 v11, v30, v31
	v_cvt_pk_bf16_f32 v13, v16, v17
	global_store_dwordx4 v[6:7], v[10:13], off offset:2048
	s_nop 1
	v_cvt_pk_bf16_f32 v10, v22, v23
	v_cvt_pk_bf16_f32 v11, v14, v15
	v_cvt_pk_bf16_f32 v12, v18, v19
	v_cvt_pk_bf16_f32 v13, v20, v21
	global_store_dwordx4 v[6:7], v[10:13], off offset:2112
	s_waitcnt vmcnt(14)
	v_lshlrev_b32_e32 v84, 16, v60
	v_and_b32_e32 v85, 0xffff0000, v60
	v_lshlrev_b32_e32 v86, 16, v64
	v_and_b32_e32 v87, 0xffff0000, v64
	v_pk_mul_f32 v[88:89], v[80:81], v[86:87]
	v_pk_mul_f32 v[80:81], v[80:81], v[84:85]
	v_lshlrev_b32_e32 v64, 16, v65
	v_and_b32_e32 v65, 0xffff0000, v65
	v_pk_fma_f32 v[88:89], v[72:73], v[84:85], v[88:89] neg_lo:[0,0,1] neg_hi:[0,0,1]
	v_pk_fma_f32 v[72:73], v[72:73], v[86:87], v[80:81]
	v_lshlrev_b32_e32 v60, 16, v61
	v_and_b32_e32 v61, 0xffff0000, v61
	v_pk_mul_f32 v[80:81], v[82:83], v[64:65]
	v_pk_mul_f32 v[88:89], v[88:89], s[86:87] op_sel_hi:[1,0]
	v_pk_fma_f32 v[80:81], v[74:75], v[60:61], v[80:81] neg_lo:[0,0,1] neg_hi:[0,0,1]
	v_pk_mul_f32 v[60:61], v[82:83], v[60:61]
	v_pk_mul_f32 v[80:81], v[80:81], s[86:87] op_sel_hi:[1,0]
	v_pk_fma_f32 v[60:61], v[74:75], v[64:65], v[60:61]
	v_lshlrev_b32_e32 v74, 16, v66
	v_and_b32_e32 v75, 0xffff0000, v66
	v_pk_mul_f32 v[64:65], v[60:61], s[86:87] op_sel_hi:[1,0]
	v_lshlrev_b32_e32 v60, 16, v62
	v_and_b32_e32 v61, 0xffff0000, v62
	v_pk_mul_f32 v[82:83], v[76:77], v[74:75]
	v_lshlrev_b32_e32 v62, 16, v67
	v_pk_fma_f32 v[82:83], v[68:69], v[60:61], v[82:83] neg_lo:[0,0,1] neg_hi:[0,0,1]
	v_pk_mul_f32 v[60:61], v[76:77], v[60:61]
	v_pk_mul_f32 v[82:83], v[82:83], s[86:87] op_sel_hi:[1,0]
	v_pk_fma_f32 v[60:61], v[68:69], v[74:75], v[60:61]
	v_pk_mul_f32 v[72:73], v[72:73], s[86:87] op_sel_hi:[1,0]
	v_pk_mul_f32 v[68:69], v[60:61], s[86:87] op_sel_hi:[1,0]
	v_lshlrev_b32_e32 v60, 16, v63
	v_and_b32_e32 v61, 0xffff0000, v63
	v_and_b32_e32 v63, 0xffff0000, v67
	v_pk_mul_f32 v[66:67], v[78:79], v[62:63]
	s_nop 0
	v_pk_fma_f32 v[66:67], v[70:71], v[60:61], v[66:67] neg_lo:[0,0,1] neg_hi:[0,0,1]
	v_pk_mul_f32 v[60:61], v[78:79], v[60:61]
	v_pk_mul_f32 v[66:67], v[66:67], s[86:87] op_sel_hi:[1,0]
	v_pk_fma_f32 v[60:61], v[70:71], v[62:63], v[60:61]
	v_cvt_pk_bf16_f32 v62, v82, v83
	v_pk_mul_f32 v[70:71], v[60:61], s[86:87] op_sel_hi:[1,0]
	v_cvt_pk_bf16_f32 v60, v88, v89
	v_cvt_pk_bf16_f32 v61, v80, v81
	v_cvt_pk_bf16_f32 v63, v66, v67
	global_store_dwordx4 v[56:57], v[60:63], off offset:2048
	s_nop 1
	v_cvt_pk_bf16_f32 v60, v72, v73
	v_cvt_pk_bf16_f32 v61, v64, v65
	v_cvt_pk_bf16_f32 v62, v68, v69
	v_cvt_pk_bf16_f32 v63, v70, v71
	global_store_dwordx4 v[56:57], v[60:63], off offset:2112
	s_waitcnt vmcnt(10)
	v_lshlrev_b32_e32 v124, 16, v100
	v_and_b32_e32 v125, 0xffff0000, v100
	v_lshlrev_b32_e32 v126, 16, v104
	v_and_b32_e32 v127, 0xffff0000, v104
	v_pk_mul_f32 v[128:129], v[120:121], v[126:127]
	v_pk_mul_f32 v[120:121], v[120:121], v[124:125]
	v_lshlrev_b32_e32 v104, 16, v105
	v_and_b32_e32 v105, 0xffff0000, v105
	v_pk_fma_f32 v[128:129], v[112:113], v[124:125], v[128:129] neg_lo:[0,0,1] neg_hi:[0,0,1]
	v_pk_fma_f32 v[112:113], v[112:113], v[126:127], v[120:121]
	v_lshlrev_b32_e32 v100, 16, v101
	v_and_b32_e32 v101, 0xffff0000, v101
	v_pk_mul_f32 v[120:121], v[122:123], v[104:105]
	v_pk_mul_f32 v[128:129], v[128:129], s[86:87] op_sel_hi:[1,0]
	v_pk_fma_f32 v[120:121], v[114:115], v[100:101], v[120:121] neg_lo:[0,0,1] neg_hi:[0,0,1]
	v_pk_mul_f32 v[100:101], v[122:123], v[100:101]
	v_pk_mul_f32 v[120:121], v[120:121], s[86:87] op_sel_hi:[1,0]
	v_pk_fma_f32 v[100:101], v[114:115], v[104:105], v[100:101]
	v_lshlrev_b32_e32 v114, 16, v106
	v_and_b32_e32 v115, 0xffff0000, v106
	v_pk_mul_f32 v[104:105], v[100:101], s[86:87] op_sel_hi:[1,0]
	v_lshlrev_b32_e32 v100, 16, v102
	v_and_b32_e32 v101, 0xffff0000, v102
	v_pk_mul_f32 v[122:123], v[116:117], v[114:115]
	v_lshlrev_b32_e32 v102, 16, v107
	v_pk_fma_f32 v[122:123], v[108:109], v[100:101], v[122:123] neg_lo:[0,0,1] neg_hi:[0,0,1]
	v_pk_mul_f32 v[100:101], v[116:117], v[100:101]
	v_pk_mul_f32 v[122:123], v[122:123], s[86:87] op_sel_hi:[1,0]
	v_pk_fma_f32 v[100:101], v[108:109], v[114:115], v[100:101]
	v_pk_mul_f32 v[112:113], v[112:113], s[86:87] op_sel_hi:[1,0]
	v_pk_mul_f32 v[108:109], v[100:101], s[86:87] op_sel_hi:[1,0]
	v_lshlrev_b32_e32 v100, 16, v103
	v_and_b32_e32 v101, 0xffff0000, v103
	v_and_b32_e32 v103, 0xffff0000, v107
	v_pk_mul_f32 v[106:107], v[118:119], v[102:103]
	s_nop 0
	v_pk_fma_f32 v[106:107], v[110:111], v[100:101], v[106:107] neg_lo:[0,0,1] neg_hi:[0,0,1]
	v_pk_mul_f32 v[100:101], v[118:119], v[100:101]
	v_pk_mul_f32 v[106:107], v[106:107], s[86:87] op_sel_hi:[1,0]
	v_pk_fma_f32 v[100:101], v[110:111], v[102:103], v[100:101]
	v_cvt_pk_bf16_f32 v102, v122, v123
	v_pk_mul_f32 v[110:111], v[100:101], s[86:87] op_sel_hi:[1,0]
	v_cvt_pk_bf16_f32 v100, v128, v129
	v_cvt_pk_bf16_f32 v101, v120, v121
	v_cvt_pk_bf16_f32 v103, v106, v107
	global_store_dwordx4 v[96:97], v[100:103], off offset:2048
	s_nop 1
	v_cvt_pk_bf16_f32 v100, v112, v113
	v_cvt_pk_bf16_f32 v101, v104, v105
	v_cvt_pk_bf16_f32 v102, v108, v109
	v_cvt_pk_bf16_f32 v103, v110, v111
	global_store_dwordx4 v[96:97], v[100:103], off offset:2112
	s_waitcnt vmcnt(6)
	v_lshlrev_b32_e32 v230, 16, v206
	v_and_b32_e32 v231, 0xffff0000, v206
	v_lshlrev_b32_e32 v232, 16, v210
	v_and_b32_e32 v233, 0xffff0000, v210
	v_pk_mul_f32 v[234:235], v[226:227], v[232:233]
	v_pk_mul_f32 v[226:227], v[226:227], v[230:231]
	v_lshlrev_b32_e32 v210, 16, v211
	v_and_b32_e32 v211, 0xffff0000, v211
	v_pk_fma_f32 v[234:235], v[218:219], v[230:231], v[234:235] neg_lo:[0,0,1] neg_hi:[0,0,1]
	v_pk_fma_f32 v[218:219], v[218:219], v[232:233], v[226:227]
	v_lshlrev_b32_e32 v206, 16, v207
	v_and_b32_e32 v207, 0xffff0000, v207
	v_pk_mul_f32 v[226:227], v[228:229], v[210:211]
	v_pk_mul_f32 v[234:235], v[234:235], s[86:87] op_sel_hi:[1,0]
	v_pk_fma_f32 v[226:227], v[220:221], v[206:207], v[226:227] neg_lo:[0,0,1] neg_hi:[0,0,1]
	v_pk_mul_f32 v[206:207], v[228:229], v[206:207]
	v_pk_mul_f32 v[226:227], v[226:227], s[86:87] op_sel_hi:[1,0]
	v_pk_fma_f32 v[206:207], v[220:221], v[210:211], v[206:207]
	v_lshlrev_b32_e32 v220, 16, v212
	v_and_b32_e32 v221, 0xffff0000, v212
	v_pk_mul_f32 v[210:211], v[206:207], s[86:87] op_sel_hi:[1,0]
	v_lshlrev_b32_e32 v206, 16, v208
	v_and_b32_e32 v207, 0xffff0000, v208
	v_pk_mul_f32 v[228:229], v[222:223], v[220:221]
	v_lshlrev_b32_e32 v208, 16, v213
	v_pk_fma_f32 v[228:229], v[214:215], v[206:207], v[228:229] neg_lo:[0,0,1] neg_hi:[0,0,1]
	v_pk_mul_f32 v[206:207], v[222:223], v[206:207]
	v_pk_mul_f32 v[228:229], v[228:229], s[86:87] op_sel_hi:[1,0]
	v_pk_fma_f32 v[206:207], v[214:215], v[220:221], v[206:207]
	v_pk_mul_f32 v[218:219], v[218:219], s[86:87] op_sel_hi:[1,0]
	v_pk_mul_f32 v[214:215], v[206:207], s[86:87] op_sel_hi:[1,0]
	v_lshlrev_b32_e32 v206, 16, v209
	v_and_b32_e32 v207, 0xffff0000, v209
	v_and_b32_e32 v209, 0xffff0000, v213
	v_pk_mul_f32 v[212:213], v[224:225], v[208:209]
	s_nop 0
	v_pk_fma_f32 v[212:213], v[216:217], v[206:207], v[212:213] neg_lo:[0,0,1] neg_hi:[0,0,1]
	v_pk_mul_f32 v[206:207], v[224:225], v[206:207]
	v_pk_mul_f32 v[212:213], v[212:213], s[86:87] op_sel_hi:[1,0]
	v_pk_fma_f32 v[206:207], v[216:217], v[208:209], v[206:207]
	v_cvt_pk_bf16_f32 v208, v228, v229
	v_pk_mul_f32 v[216:217], v[206:207], s[86:87] op_sel_hi:[1,0]
	v_cvt_pk_bf16_f32 v206, v234, v235
	v_cvt_pk_bf16_f32 v207, v226, v227
	v_cvt_pk_bf16_f32 v209, v212, v213
	global_store_dwordx4 v[202:203], v[206:209], off offset:2048
	s_nop 1
	v_cvt_pk_bf16_f32 v206, v218, v219
	v_cvt_pk_bf16_f32 v207, v210, v211
	v_cvt_pk_bf16_f32 v208, v214, v215
	v_cvt_pk_bf16_f32 v209, v216, v217
	global_store_dwordx4 v[202:203], v[206:209], off offset:2112
	s_mov_b32 s1, 0x800
	v_and_b32_e32 v0, 8, v8
	s_lshl_b32 s4, s0, 1
	v_bfe_u32 v3, v8, 2, 1
	v_cmp_eq_u32_e32 vcc, 0, v0
	v_mov_b32_e32 v7, v1
	v_or_b32_e32 v10, s4, v3
	v_cndmask_b32_e32 v0, v186, v192, vcc
	v_cndmask_b32_e32 v6, v193, v194, vcc
	v_mov_b32_e32 v11, v1
	v_lshl_add_u64 v[4:5], s[50:51], 0, v[0:1]
	v_lshlrev_b32_e32 v0, 7, v3
	v_lshlrev_b64 v[10:11], 18, v[10:11]
	v_lshl_add_u64 v[6:7], s[64:65], 0, v[6:7]
	v_lshl_add_u64 v[4:5], v[4:5], 0, v[0:1]
	v_lshlrev_b32_e32 v0, 1, v2
	v_lshl_add_u64 v[6:7], v[6:7], 0, v[10:11]
	s_mov_b32 s5, 0
	v_lshl_add_u64 v[4:5], v[4:5], 0, v[0:1]
	v_lshl_add_u64 v[6:7], v[6:7], 0, v[0:1]
	s_mov_b64 s[0:1], -1

.LBB0_1487:
	s_mov_b32 s1, 0x0
	s_mov_b32 s0, 0x0
	s_cmp_lt_u32 s1, 2
	s_cselect_b32 s54, s81, 0x1100
	s_and_b32 s3, s0, 64
	v_lshl_add_u64 v[8:9], v[2:3], 0, s[54:55]
	s_lshl_b32 s54, s3, 1
	v_lshl_add_u64 v[8:9], v[8:9], 0, s[54:55]
	v_lshl_add_u64 v[8:9], v[8:9], 0, v[0:1]
	global_load_dwordx4 v[8:11], v[8:9], off
	s_mov_b32 s1, 0x1
	s_mov_b32 s0, 0x40
	s_cmp_lt_u32 s1, 2
	s_cselect_b32 s54, s81, 0x1100
	s_and_b32 s3, s0, 64
	v_lshl_add_u64 v[58:59], v[2:3], 0, s[54:55]
	s_lshl_b32 s54, s3, 1
	v_lshl_add_u64 v[58:59], v[58:59], 0, s[54:55]
	v_lshl_add_u64 v[58:59], v[58:59], 0, v[0:1]
	global_load_dwordx4 v[58:61], v[58:59], off
	s_mov_b32 s1, 0x2
	s_mov_b32 s0, 0x80
	s_cmp_lt_u32 s1, 2
	s_cselect_b32 s54, s81, 0x1100
	s_and_b32 s3, s0, 64
	v_lshl_add_u64 v[98:99], v[2:3], 0, s[54:55]
	s_lshl_b32 s54, s3, 1
	v_lshl_add_u64 v[98:99], v[98:99], 0, s[54:55]
	v_lshl_add_u64 v[98:99], v[98:99], 0, v[0:1]
	global_load_dwordx4 v[98:101], v[98:99], off
	s_mov_b32 s1, 0x3
	s_mov_b32 s0, 0xc0
	s_cmp_lt_u32 s1, 2
	s_cselect_b32 s54, s81, 0x1100
	s_and_b32 s3, s0, 64
	v_lshl_add_u64 v[204:205], v[2:3], 0, s[54:55]
	s_lshl_b32 s54, s3, 1
	v_lshl_add_u64 v[204:205], v[204:205], 0, s[54:55]
	v_lshl_add_u64 v[204:205], v[204:205], 0, v[0:1]
	global_load_dwordx4 v[204:207], v[204:205], off
	s_waitcnt vmcnt(3)
	ds_write_b128 v5, v[8:11]
	v_add_u32_e32 v5, 0x2400, v5
	s_waitcnt vmcnt(2)
	ds_write_b128 v5, v[58:61]
	v_add_u32_e32 v5, 0x2400, v5
	s_waitcnt vmcnt(1)
	ds_write_b128 v5, v[98:101]
	v_add_u32_e32 v5, 0x2400, v5
	s_waitcnt vmcnt(0)
	ds_write_b128 v5, v[204:207]
	v_add_u32_e32 v5, 0x2400, v5
	s_mov_b32 s1, 0x4
	s_mov_b32 s0, 0x100
	v_ashrrev_i32_e32 v5, 31, v4
	v_lshlrev_b64 v[2:3], 12, v[4:5]
	v_mul_u32_u24_e32 v5, 0x480, v6
	v_lshlrev_b32_e32 v4, 1, v4
	v_add3_u32 v4, v5, v4, 0
	s_mov_b32 s3, 0
	s_lshl_b32 s0, s16, 1
	s_waitcnt lgkmcnt(0)
	s_barrier

.LBB0_1555:
	s_mov_b32 s1, 0x0
	v_add_u32_e32 v0, s1, v8
	v_ashrrev_i32_e32 v0, 5, v0
	v_add_u32_e32 v3, s16, v0
	v_lshl_or_b32 v18, v3, 5, v2
	v_add_u32_e32 v0, s2, v0
	v_ashrrev_i32_e32 v19, 31, v18
	v_mad_i64_i32 v[6:7], s[4:5], v0, s84, v[4:5]
	v_lshlrev_b64 v[18:19], 2, v[18:19]
	global_load_dwordx4 v[10:13], v[6:7], off offset:2048
	global_load_dwordx4 v[14:17], v[6:7], off offset:2112
	v_lshl_add_u64 v[22:23], s[8:9], 0, v[18:19]
	v_lshl_add_u64 v[30:31], s[10:11], 0, v[18:19]
	global_load_dwordx4 v[18:21], v[22:23], off offset:16
	s_nop 0
	global_load_dwordx4 v[22:25], v[22:23], off
	s_nop 0
	global_load_dwordx4 v[26:29], v[30:31], off offset:16
	s_nop 0
	global_load_dwordx4 v[30:33], v[30:31], off
	s_mov_b32 s1, 0x200
	v_add_u32_e32 v50, s1, v8
	v_ashrrev_i32_e32 v50, 5, v50
	v_add_u32_e32 v53, s16, v50
	v_lshl_or_b32 v68, v53, 5, v2
	v_add_u32_e32 v50, s2, v50
	v_ashrrev_i32_e32 v69, 31, v68
	v_mad_i64_i32 v[56:57], s[4:5], v50, s84, v[4:5]
	v_lshlrev_b64 v[68:69], 2, v[68:69]
	global_load_dwordx4 v[60:63], v[56:57], off offset:2048
	global_load_dwordx4 v[64:67], v[56:57], off offset:2112
	v_lshl_add_u64 v[72:73], s[8:9], 0, v[68:69]
	v_lshl_add_u64 v[80:81], s[10:11], 0, v[68:69]
	global_load_dwordx4 v[68:71], v[72:73], off offset:16
	s_nop 0
	global_load_dwordx4 v[72:75], v[72:73], off
	s_nop 0
	global_load_dwordx4 v[76:79], v[80:81], off offset:16
	s_nop 0
	global_load_dwordx4 v[80:83], v[80:81], off
	s_mov_b32 s1, 0x400
	v_add_u32_e32 v90, s1, v8
	v_ashrrev_i32_e32 v90, 5, v90
	v_add_u32_e32 v93, s16, v90
	v_lshl_or_b32 v108, v93, 5, v2
	v_add_u32_e32 v90, s2, v90
	v_ashrrev_i32_e32 v109, 31, v108
	v_mad_i64_i32 v[96:97], s[4:5], v90, s84, v[4:5]
	v_lshlrev_b64 v[108:109], 2, v[108:109]
	global_load_dwordx4 v[100:103], v[96:97], off offset:2048
	global_load_dwordx4 v[104:107], v[96:97], off offset:2112
	v_lshl_add_u64 v[112:113], s[8:9], 0, v[108:109]
	v_lshl_add_u64 v[120:121], s[10:11], 0, v[108:109]
	global_load_dwordx4 v[108:111], v[112:113], off offset:16
	s_nop 0
	global_load_dwordx4 v[112:115], v[112:113], off
	s_nop 0
	global_load_dwordx4 v[116:119], v[120:121], off offset:16
	s_nop 0
	global_load_dwordx4 v[120:123], v[120:121], off
	s_mov_b32 s1, 0x600
	v_add_u32_e32 v196, s1, v8
	v_ashrrev_i32_e32 v196, 5, v196
	v_add_u32_e32 v199, s16, v196
	v_lshl_or_b32 v214, v199, 5, v2
	v_add_u32_e32 v196, s2, v196
	v_ashrrev_i32_e32 v215, 31, v214
	v_mad_i64_i32 v[202:203], s[4:5], v196, s84, v[4:5]
	v_lshlrev_b64 v[214:215], 2, v[214:215]
	global_load_dwordx4 v[206:209], v[202:203], off offset:2048
	global_load_dwordx4 v[210:213], v[202:203], off offset:2112
	v_lshl_add_u64 v[218:219], s[8:9], 0, v[214:215]
	v_lshl_add_u64 v[226:227], s[10:11], 0, v[214:215]
	global_load_dwordx4 v[214:217], v[218:219], off offset:16
	s_nop 0
	global_load_dwordx4 v[218:221], v[218:219], off
	s_nop 0
	global_load_dwordx4 v[222:225], v[226:227], off offset:16
	s_nop 0
	global_load_dwordx4 v[226:229], v[226:227], off
	s_waitcnt vmcnt(18)
	v_lshlrev_b32_e32 v34, 16, v10
	v_and_b32_e32 v35, 0xffff0000, v10
	v_lshlrev_b32_e32 v36, 16, v14
	v_and_b32_e32 v37, 0xffff0000, v14
	v_pk_mul_f32 v[38:39], v[30:31], v[36:37]
	v_pk_mul_f32 v[30:31], v[30:31], v[34:35]
	v_lshlrev_b32_e32 v14, 16, v15
	v_and_b32_e32 v15, 0xffff0000, v15
	v_pk_fma_f32 v[38:39], v[22:23], v[34:35], v[38:39] neg_lo:[0,0,1] neg_hi:[0,0,1]
	v_pk_fma_f32 v[22:23], v[22:23], v[36:37], v[30:31]
	v_lshlrev_b32_e32 v10, 16, v11
	v_and_b32_e32 v11, 0xffff0000, v11
	v_pk_mul_f32 v[30:31], v[32:33], v[14:15]
	v_pk_mul_f32 v[38:39], v[38:39], s[86:87] op_sel_hi:[1,0]
	v_pk_fma_f32 v[30:31], v[24:25], v[10:11], v[30:31] neg_lo:[0,0,1] neg_hi:[0,0,1]
	v_pk_mul_f32 v[10:11], v[32:33], v[10:11]
	v_pk_mul_f32 v[30:31], v[30:31], s[86:87] op_sel_hi:[1,0]
	v_pk_fma_f32 v[10:11], v[24:25], v[14:15], v[10:11]
	v_lshlrev_b32_e32 v24, 16, v16
	v_and_b32_e32 v25, 0xffff0000, v16
	v_pk_mul_f32 v[14:15], v[10:11], s[86:87] op_sel_hi:[1,0]
	v_lshlrev_b32_e32 v10, 16, v12
	v_and_b32_e32 v11, 0xffff0000, v12
	v_pk_mul_f32 v[32:33], v[26:27], v[24:25]
	v_lshlrev_b32_e32 v12, 16, v17
	v_pk_fma_f32 v[32:33], v[18:19], v[10:11], v[32:33] neg_lo:[0,0,1] neg_hi:[0,0,1]
	v_pk_mul_f32 v[10:11], v[26:27], v[10:11]
	v_pk_mul_f32 v[32:33], v[32:33], s[86:87] op_sel_hi:[1,0]
	v_pk_fma_f32 v[10:11], v[18:19], v[24:25], v[10:11]
	v_pk_mul_f32 v[22:23], v[22:23], s[86:87] op_sel_hi:[1,0]
	v_pk_mul_f32 v[18:19], v[10:11], s[86:87] op_sel_hi:[1,0]
	v_lshlrev_b32_e32 v10, 16, v13
	v_and_b32_e32 v11, 0xffff0000, v13
	v_and_b32_e32 v13, 0xffff0000, v17
	v_pk_mul_f32 v[16:17], v[28:29], v[12:13]
	s_nop 0
	v_pk_fma_f32 v[16:17], v[20:21], v[10:11], v[16:17] neg_lo:[0,0,1] neg_hi:[0,0,1]
	v_pk_mul_f32 v[10:11], v[28:29], v[10:11]
	v_pk_mul_f32 v[16:17], v[16:17], s[86:87] op_sel_hi:[1,0]
	v_pk_fma_f32 v[10:11], v[20:21], v[12:13], v[10:11]
	v_cvt_pk_bf16_f32 v12, v32, v33
	v_pk_mul_f32 v[20:21], v[10:11], s[86:87] op_sel_hi:[1,0]
	v_cvt_pk_bf16_f32 v10, v38, v39
	v_cvt_pk_bf16_f32 v11, v30, v31
	v_cvt_pk_bf16_f32 v13, v16, v17
	global_store_dwordx4 v[6:7], v[10:13], off offset:2048
	s_nop 1
	v_cvt_pk_bf16_f32 v10, v22, v23
	v_cvt_pk_bf16_f32 v11, v14, v15
	v_cvt_pk_bf16_f32 v12, v18, v19
	v_cvt_pk_bf16_f32 v13, v20, v21
	global_store_dwordx4 v[6:7], v[10:13], off offset:2112
	s_waitcnt vmcnt(14)
	v_lshlrev_b32_e32 v84, 16, v60
	v_and_b32_e32 v85, 0xffff0000, v60
	v_lshlrev_b32_e32 v86, 16, v64
	v_and_b32_e32 v87, 0xffff0000, v64
	v_pk_mul_f32 v[88:89], v[80:81], v[86:87]
	v_pk_mul_f32 v[80:81], v[80:81], v[84:85]
	v_lshlrev_b32_e32 v64, 16, v65
	v_and_b32_e32 v65, 0xffff0000, v65
	v_pk_fma_f32 v[88:89], v[72:73], v[84:85], v[88:89] neg_lo:[0,0,1] neg_hi:[0,0,1]
	v_pk_fma_f32 v[72:73], v[72:73], v[86:87], v[80:81]
	v_lshlrev_b32_e32 v60, 16, v61
	v_and_b32_e32 v61, 0xffff0000, v61
	v_pk_mul_f32 v[80:81], v[82:83], v[64:65]
	v_pk_mul_f32 v[88:89], v[88:89], s[86:87] op_sel_hi:[1,0]
	v_pk_fma_f32 v[80:81], v[74:75], v[60:61], v[80:81] neg_lo:[0,0,1] neg_hi:[0,0,1]
	v_pk_mul_f32 v[60:61], v[82:83], v[60:61]
	v_pk_mul_f32 v[80:81], v[80:81], s[86:87] op_sel_hi:[1,0]
	v_pk_fma_f32 v[60:61], v[74:75], v[64:65], v[60:61]
	v_lshlrev_b32_e32 v74, 16, v66
	v_and_b32_e32 v75, 0xffff0000, v66
	v_pk_mul_f32 v[64:65], v[60:61], s[86:87] op_sel_hi:[1,0]
	v_lshlrev_b32_e32 v60, 16, v62
	v_and_b32_e32 v61, 0xffff0000, v62
	v_pk_mul_f32 v[82:83], v[76:77], v[74:75]
	v_lshlrev_b32_e32 v62, 16, v67
	v_pk_fma_f32 v[82:83], v[68:69], v[60:61], v[82:83] neg_lo:[0,0,1] neg_hi:[0,0,1]
	v_pk_mul_f32 v[60:61], v[76:77], v[60:61]
	v_pk_mul_f32 v[82:83], v[82:83], s[86:87] op_sel_hi:[1,0]
	v_pk_fma_f32 v[60:61], v[68:69], v[74:75], v[60:61]
	v_pk_mul_f32 v[72:73], v[72:73], s[86:87] op_sel_hi:[1,0]
	v_pk_mul_f32 v[68:69], v[60:61], s[86:87] op_sel_hi:[1,0]
	v_lshlrev_b32_e32 v60, 16, v63
	v_and_b32_e32 v61, 0xffff0000, v63
	v_and_b32_e32 v63, 0xffff0000, v67
	v_pk_mul_f32 v[66:67], v[78:79], v[62:63]
	s_nop 0
	v_pk_fma_f32 v[66:67], v[70:71], v[60:61], v[66:67] neg_lo:[0,0,1] neg_hi:[0,0,1]
	v_pk_mul_f32 v[60:61], v[78:79], v[60:61]
	v_pk_mul_f32 v[66:67], v[66:67], s[86:87] op_sel_hi:[1,0]
	v_pk_fma_f32 v[60:61], v[70:71], v[62:63], v[60:61]
	v_cvt_pk_bf16_f32 v62, v82, v83
	v_pk_mul_f32 v[70:71], v[60:61], s[86:87] op_sel_hi:[1,0]
	v_cvt_pk_bf16_f32 v60, v88, v89
	v_cvt_pk_bf16_f32 v61, v80, v81
	v_cvt_pk_bf16_f32 v63, v66, v67
	global_store_dwordx4 v[56:57], v[60:63], off offset:2048
	s_nop 1
	v_cvt_pk_bf16_f32 v60, v72, v73
	v_cvt_pk_bf16_f32 v61, v64, v65
	v_cvt_pk_bf16_f32 v62, v68, v69
	v_cvt_pk_bf16_f32 v63, v70, v71
	global_store_dwordx4 v[56:57], v[60:63], off offset:2112
	s_waitcnt vmcnt(10)
	v_lshlrev_b32_e32 v124, 16, v100
	v_and_b32_e32 v125, 0xffff0000, v100
	v_lshlrev_b32_e32 v126, 16, v104
	v_and_b32_e32 v127, 0xffff0000, v104
	v_pk_mul_f32 v[128:129], v[120:121], v[126:127]
	v_pk_mul_f32 v[120:121], v[120:121], v[124:125]
	v_lshlrev_b32_e32 v104, 16, v105
	v_and_b32_e32 v105, 0xffff0000, v105
	v_pk_fma_f32 v[128:129], v[112:113], v[124:125], v[128:129] neg_lo:[0,0,1] neg_hi:[0,0,1]
	v_pk_fma_f32 v[112:113], v[112:113], v[126:127], v[120:121]
	v_lshlrev_b32_e32 v100, 16, v101
	v_and_b32_e32 v101, 0xffff0000, v101
	v_pk_mul_f32 v[120:121], v[122:123], v[104:105]
	v_pk_mul_f32 v[128:129], v[128:129], s[86:87] op_sel_hi:[1,0]
	v_pk_fma_f32 v[120:121], v[114:115], v[100:101], v[120:121] neg_lo:[0,0,1] neg_hi:[0,0,1]
	v_pk_mul_f32 v[100:101], v[122:123], v[100:101]
	v_pk_mul_f32 v[120:121], v[120:121], s[86:87] op_sel_hi:[1,0]
	v_pk_fma_f32 v[100:101], v[114:115], v[104:105], v[100:101]
	v_lshlrev_b32_e32 v114, 16, v106
	v_and_b32_e32 v115, 0xffff0000, v106
	v_pk_mul_f32 v[104:105], v[100:101], s[86:87] op_sel_hi:[1,0]
	v_lshlrev_b32_e32 v100, 16, v102
	v_and_b32_e32 v101, 0xffff0000, v102
	v_pk_mul_f32 v[122:123], v[116:117], v[114:115]
	v_lshlrev_b32_e32 v102, 16, v107
	v_pk_fma_f32 v[122:123], v[108:109], v[100:101], v[122:123] neg_lo:[0,0,1] neg_hi:[0,0,1]
	v_pk_mul_f32 v[100:101], v[116:117], v[100:101]
	v_pk_mul_f32 v[122:123], v[122:123], s[86:87] op_sel_hi:[1,0]
	v_pk_fma_f32 v[100:101], v[108:109], v[114:115], v[100:101]
	v_pk_mul_f32 v[112:113], v[112:113], s[86:87] op_sel_hi:[1,0]
	v_pk_mul_f32 v[108:109], v[100:101], s[86:87] op_sel_hi:[1,0]
	v_lshlrev_b32_e32 v100, 16, v103
	v_and_b32_e32 v101, 0xffff0000, v103
	v_and_b32_e32 v103, 0xffff0000, v107
	v_pk_mul_f32 v[106:107], v[118:119], v[102:103]
	s_nop 0
	v_pk_fma_f32 v[106:107], v[110:111], v[100:101], v[106:107] neg_lo:[0,0,1] neg_hi:[0,0,1]
	v_pk_mul_f32 v[100:101], v[118:119], v[100:101]
	v_pk_mul_f32 v[106:107], v[106:107], s[86:87] op_sel_hi:[1,0]
	v_pk_fma_f32 v[100:101], v[110:111], v[102:103], v[100:101]
	v_cvt_pk_bf16_f32 v102, v122, v123
	v_pk_mul_f32 v[110:111], v[100:101], s[86:87] op_sel_hi:[1,0]
	v_cvt_pk_bf16_f32 v100, v128, v129
	v_cvt_pk_bf16_f32 v101, v120, v121
	v_cvt_pk_bf16_f32 v103, v106, v107
	global_store_dwordx4 v[96:97], v[100:103], off offset:2048
	s_nop 1
	v_cvt_pk_bf16_f32 v100, v112, v113
	v_cvt_pk_bf16_f32 v101, v104, v105
	v_cvt_pk_bf16_f32 v102, v108, v109
	v_cvt_pk_bf16_f32 v103, v110, v111
	global_store_dwordx4 v[96:97], v[100:103], off offset:2112
	s_waitcnt vmcnt(6)
	v_lshlrev_b32_e32 v230, 16, v206
	v_and_b32_e32 v231, 0xffff0000, v206
	v_lshlrev_b32_e32 v232, 16, v210
	v_and_b32_e32 v233, 0xffff0000, v210
	v_pk_mul_f32 v[234:235], v[226:227], v[232:233]
	v_pk_mul_f32 v[226:227], v[226:227], v[230:231]
	v_lshlrev_b32_e32 v210, 16, v211
	v_and_b32_e32 v211, 0xffff0000, v211
	v_pk_fma_f32 v[234:235], v[218:219], v[230:231], v[234:235] neg_lo:[0,0,1] neg_hi:[0,0,1]
	v_pk_fma_f32 v[218:219], v[218:219], v[232:233], v[226:227]
	v_lshlrev_b32_e32 v206, 16, v207
	v_and_b32_e32 v207, 0xffff0000, v207
	v_pk_mul_f32 v[226:227], v[228:229], v[210:211]
	v_pk_mul_f32 v[234:235], v[234:235], s[86:87] op_sel_hi:[1,0]
	v_pk_fma_f32 v[226:227], v[220:221], v[206:207], v[226:227] neg_lo:[0,0,1] neg_hi:[0,0,1]
	v_pk_mul_f32 v[206:207], v[228:229], v[206:207]
	v_pk_mul_f32 v[226:227], v[226:227], s[86:87] op_sel_hi:[1,0]
	v_pk_fma_f32 v[206:207], v[220:221], v[210:211], v[206:207]
	v_lshlrev_b32_e32 v220, 16, v212
	v_and_b32_e32 v221, 0xffff0000, v212
	v_pk_mul_f32 v[210:211], v[206:207], s[86:87] op_sel_hi:[1,0]
	v_lshlrev_b32_e32 v206, 16, v208
	v_and_b32_e32 v207, 0xffff0000, v208
	v_pk_mul_f32 v[228:229], v[222:223], v[220:221]
	v_lshlrev_b32_e32 v208, 16, v213
	v_pk_fma_f32 v[228:229], v[214:215], v[206:207], v[228:229] neg_lo:[0,0,1] neg_hi:[0,0,1]
	v_pk_mul_f32 v[206:207], v[222:223], v[206:207]
	v_pk_mul_f32 v[228:229], v[228:229], s[86:87] op_sel_hi:[1,0]
	v_pk_fma_f32 v[206:207], v[214:215], v[220:221], v[206:207]
	v_pk_mul_f32 v[218:219], v[218:219], s[86:87] op_sel_hi:[1,0]
	v_pk_mul_f32 v[214:215], v[206:207], s[86:87] op_sel_hi:[1,0]
	v_lshlrev_b32_e32 v206, 16, v209
	v_and_b32_e32 v207, 0xffff0000, v209
	v_and_b32_e32 v209, 0xffff0000, v213
	v_pk_mul_f32 v[212:213], v[224:225], v[208:209]
	s_nop 0
	v_pk_fma_f32 v[212:213], v[216:217], v[206:207], v[212:213] neg_lo:[0,0,1] neg_hi:[0,0,1]
	v_pk_mul_f32 v[206:207], v[224:225], v[206:207]
	v_pk_mul_f32 v[212:213], v[212:213], s[86:87] op_sel_hi:[1,0]
	v_pk_fma_f32 v[206:207], v[216:217], v[208:209], v[206:207]
	v_cvt_pk_bf16_f32 v208, v228, v229
	v_pk_mul_f32 v[216:217], v[206:207], s[86:87] op_sel_hi:[1,0]
	v_cvt_pk_bf16_f32 v206, v234, v235
	v_cvt_pk_bf16_f32 v207, v226, v227
	v_cvt_pk_bf16_f32 v209, v212, v213
	global_store_dwordx4 v[202:203], v[206:209], off offset:2048
	s_nop 1
	v_cvt_pk_bf16_f32 v206, v218, v219
	v_cvt_pk_bf16_f32 v207, v210, v211
	v_cvt_pk_bf16_f32 v208, v214, v215
	v_cvt_pk_bf16_f32 v209, v216, v217
	global_store_dwordx4 v[202:203], v[206:209], off offset:2112
	s_mov_b32 s1, 0x800
	s_lshl_b32 s3, s0, 1
	v_bfe_u32 v3, v8, 2, 1
	v_and_b32_e32 v0, 8, v8
	v_cmp_eq_u32_e32 vcc, 0, v0
	v_or_b32_e32 v10, s3, v3
	v_mov_b32_e32 v7, v1
	v_cndmask_b32_e32 v0, v186, v192, vcc
	v_cndmask_b32_e32 v6, v193, v194, vcc
	v_ashrrev_i32_e32 v11, 31, v10
	v_lshl_add_u64 v[4:5], s[50:51], 0, v[0:1]
	v_lshlrev_b32_e32 v0, 7, v3
	v_lshlrev_b64 v[10:11], 18, v[10:11]
	v_lshl_add_u64 v[6:7], s[64:65], 0, v[6:7]
	v_lshl_add_u64 v[4:5], v[4:5], 0, v[0:1]
	v_lshlrev_b32_e32 v0, 1, v2
	v_lshl_add_u64 v[6:7], v[6:7], 0, v[10:11]
	s_mov_b32 s4, 0
	v_lshl_add_u64 v[4:5], v[4:5], 0, v[0:1]
	v_lshl_add_u64 v[6:7], v[6:7], 0, v[0:1]
	s_mov_b64 s[0:1], -1

.LBB0_1559:
	s_mov_b32 s1, 0x0
	s_mov_b32 s0, 0x0
	s_cmp_lt_u32 s1, 2
	s_cselect_b32 s54, s81, 0x1100
	s_and_b32 s2, s0, 64
	v_lshl_add_u64 v[8:9], v[2:3], 0, s[54:55]
	s_lshl_b32 s54, s2, 1
	v_lshl_add_u64 v[8:9], v[8:9], 0, s[54:55]
	v_lshl_add_u64 v[8:9], v[8:9], 0, v[0:1]
	global_load_dwordx4 v[8:11], v[8:9], off
	s_mov_b32 s1, 0x1
	s_mov_b32 s0, 0x40
	s_cmp_lt_u32 s1, 2
	s_cselect_b32 s54, s81, 0x1100
	s_and_b32 s2, s0, 64
	v_lshl_add_u64 v[58:59], v[2:3], 0, s[54:55]
	s_lshl_b32 s54, s2, 1
	v_lshl_add_u64 v[58:59], v[58:59], 0, s[54:55]
	v_lshl_add_u64 v[58:59], v[58:59], 0, v[0:1]
	global_load_dwordx4 v[58:61], v[58:59], off
	s_mov_b32 s1, 0x2
	s_mov_b32 s0, 0x80
	s_cmp_lt_u32 s1, 2
	s_cselect_b32 s54, s81, 0x1100
	s_and_b32 s2, s0, 64
	v_lshl_add_u64 v[98:99], v[2:3], 0, s[54:55]
	s_lshl_b32 s54, s2, 1
	v_lshl_add_u64 v[98:99], v[98:99], 0, s[54:55]
	v_lshl_add_u64 v[98:99], v[98:99], 0, v[0:1]
	global_load_dwordx4 v[98:101], v[98:99], off
	s_mov_b32 s1, 0x3
	s_mov_b32 s0, 0xc0
	s_cmp_lt_u32 s1, 2
	s_cselect_b32 s54, s81, 0x1100
	s_and_b32 s2, s0, 64
	v_lshl_add_u64 v[204:205], v[2:3], 0, s[54:55]
	s_lshl_b32 s54, s2, 1
	v_lshl_add_u64 v[204:205], v[204:205], 0, s[54:55]
	v_lshl_add_u64 v[204:205], v[204:205], 0, v[0:1]
	global_load_dwordx4 v[204:207], v[204:205], off
	s_waitcnt vmcnt(3)
	ds_write_b128 v5, v[8:11]
	v_add_u32_e32 v5, 0x2400, v5
	s_waitcnt vmcnt(2)
	ds_write_b128 v5, v[58:61]
	v_add_u32_e32 v5, 0x2400, v5
	s_waitcnt vmcnt(1)
	ds_write_b128 v5, v[98:101]
	v_add_u32_e32 v5, 0x2400, v5
	s_waitcnt vmcnt(0)
	ds_write_b128 v5, v[204:207]
	v_add_u32_e32 v5, 0x2400, v5
	s_mov_b32 s1, 0x4
	s_mov_b32 s0, 0x100
	v_ashrrev_i32_e32 v5, 31, v4
	v_lshlrev_b64 v[2:3], 12, v[4:5]
	v_mul_u32_u24_e32 v5, 0x480, v6
	v_lshlrev_b32_e32 v4, 1, v4
	v_add3_u32 v4, v5, v4, 0
	s_mov_b32 s0, 0
	s_lshl_b32 s54, s16, 1
	s_waitcnt lgkmcnt(0)
	s_barrier
